# v118 + differential-attention loop unrolled by two (P register sets exchanged) + all hot loop heads incl. the second copy pinned to 64-byte phase
# speedup vs baseline: 1.0069x; 1.0069x over previous
.LBB0_571:
	s_mul_hi_u32 s40, s72, 0xaaaaaaab
	s_lshr_b32 s40, s40, 1
	s_mul_i32 s40, s40, 0xd800
	s_bitcmp1_b32 s72, 0
	v_subrev_u32_e32 v80, s40, v222
	s_cselect_b32 s40, 0x4400, 0
	v_add_u32_e32 v81, s40, v234
	s_add_i32 s40, s73, 0
	v_add_u32_e32 v80, s40, v80
	s_waitcnt vmcnt(3)
	ds_write_b128 v81, v[144:147]
	s_waitcnt vmcnt(2)
	ds_write_b128 v80, v[148:151] offset:53248
	s_waitcnt vmcnt(1)
	ds_write_b128 v81, v[152:155] offset:8704
	s_waitcnt vmcnt(0)
	ds_write_b128 v80, v[156:159] offset:62464
	s_branch .Ldfu_554
	s_nop 0
	s_nop 0
	s_nop 0
	s_nop 0
	s_nop 0
	s_nop 0
	s_nop 0
	s_nop 0
	s_nop 0
	s_nop 0
	s_nop 0
	s_nop 0
	s_nop 0

.LBB0_585:
	s_and_b32 s4, s63, 7
	s_lshl_b32 s5, s4, 2
	v_mov_b32_e32 v6, v225
	s_or_b32 s71, s5, 2
	s_and_b32 s42, s3, 7
	v_readfirstlane_b32 s5, v6
	s_ashr_i32 s64, s5, 6
	s_lshl_b32 s65, s4, 8
	s_ashr_i32 s4, s3, 6
	s_lshl_b32 s5, s42, 8
	s_lshl_b32 s66, s64, 5
	s_add_i32 s66, s66, s5
	s_ashr_i32 s5, s4, 31
	s_bfe_u32 s8, s3, 0x30003
	v_and_b32_e32 v7, 31, v6
	s_lshl_b64 s[38:39], s[4:5], 11
	s_lshl_b32 s4, s4, 3
	s_waitcnt vmcnt(2)
	v_or_b32_e32 v150, s66, v7
	s_or_b32 s4, s4, s8
	s_ashr_i32 s5, s4, 31
	v_ashrrev_i32_e32 v151, 31, v150
	s_lshl_b64 s[4:5], s[4:5], 19
	v_lshl_add_u64 v[2:3], s[38:39], 0, v[150:151]
	s_add_u32 s6, s14, s4
	v_mad_u64_u32 v[4:5], s[40:41], v2, s44, v[146:147]
	v_bfe_u32 v8, v6, 5, 1
	s_addc_u32 s7, s15, s5
	v_mad_i32_i24 v5, v3, s44, v5
	s_lshl_b32 s67, s8, 7
	s_lshl_b32 s8, s8, 8
	v_lshl_add_u64 v[2:3], v[4:5], 0, s[8:9]
	v_lshlrev_b32_e32 v0, 4, v8
	v_lshl_add_u64 v[2:3], v[2:3], 0, v[0:1]
	global_load_dwordx4 v[98:101], v[2:3], off
	global_load_dwordx4 v[102:105], v[2:3], off offset:32
	global_load_dwordx4 v[106:109], v[2:3], off offset:64
	global_load_dwordx4 v[110:113], v[2:3], off offset:96
	global_load_dwordx4 v[114:117], v[2:3], off offset:128
	global_load_dwordx4 v[118:121], v[2:3], off offset:160
	global_load_dwordx4 v[122:125], v[2:3], off offset:192
	global_load_dwordx4 v[126:129], v[2:3], off offset:224
	v_lshlrev_b32_e32 v2, 3, v6
	s_add_u32 s4, s81, s4
	v_ashrrev_i32_e32 v3, 31, v2
	s_addc_u32 s5, s82, s5
	v_lshlrev_b64 v[2:3], 1, v[2:3]
	v_mov_b32_e32 v228, v2
	v_add_u32_e32 v229, 0x2000, v2
	s_waitcnt vmcnt(9)
	s_mov_b64 s[90:91], s[4:5]
	v_lshl_add_u64 v[154:155], s[4:5], 0, v[2:3]
	s_lshl_b32 s4, s42, 16
	s_mov_b64 s[88:89], s[6:7]
	v_lshl_add_u64 v[152:153], s[6:7], 0, v[2:3]
	s_or_b32 s8, s4, 0xc000
	v_lshl_add_u64 v[2:3], v[152:153], 0, s[8:9]
	s_barrier
	v_lshl_add_u64 v[4:5], v[154:155], 0, s[8:9]
	global_load_dwordx4 v[130:133], v[2:3], off
	global_load_dwordx4 v[134:137], v[4:5], off
	v_add_co_u32_e32 v2, vcc, s46, v2
	v_and_b32_e32 v149, 63, v6
	s_nop 0
	v_addc_co_u32_e32 v3, vcc, 0, v3, vcc
	v_add_co_u32_e32 v4, vcc, s46, v4
	v_mul_u32_u24_e32 v197, 0x110, v7
	s_nop 0
	v_addc_co_u32_e32 v5, vcc, 0, v5, vcc
	global_load_dwordx4 v[138:141], v[2:3], off
	global_load_dwordx4 v[142:145], v[4:5], off
	v_lshlrev_b32_e32 v2, 4, v6
	v_lshrrev_b32_e32 v3, 3, v6
	v_lshrrev_b32_e32 v4, 4, v6
	v_and_b32_e32 v148, 0xf0, v2
	v_and_b32_e32 v2, 0x70, v2
	s_waitcnt vmcnt(12)
	v_mad_u64_u32 v[156:157], s[4:5], v4, s47, v[148:149]
	v_mad_u64_u32 v[158:159], s[4:5], v3, s48, v[2:3]
	v_lshlrev_b32_e32 v5, 7, v7
	v_add3_u32 v157, 0, v197, v0
	v_add_u32_e32 v0, 0, v156
	v_add_u32_e32 v2, 0, v158
	v_mov_b32_e32 v14, v1
	v_mov_b32_e32 v15, v1
	v_lshlrev_b32_e32 v151, 3, v8
	s_lshl_b32 s4, s64, 2
	v_lshlrev_b32_e32 v159, 2, v8
	v_sub_u32_e32 v198, v157, v5
	v_mov_b32_e32 v3, v1
	v_mov_b32_e32 v4, v1
	v_mov_b32_e32 v5, v1
	v_mov_b32_e32 v6, v1
	v_mov_b32_e32 v7, v1
	v_mov_b32_e32 v8, v1
	v_mov_b32_e32 v9, v1
	v_mov_b32_e32 v10, v1
	v_mov_b32_e32 v11, v1
	v_mov_b32_e32 v12, v1
	v_mov_b32_e32 v13, v1
	s_add_i32 s69, s4, 0
	v_cmp_eq_u32_e64 s[6:7], 0, v149
	s_or_b32 s68, s66, 30
	s_add_i32 s69, s69, 0x11800
	v_cmp_gt_u32_e64 s[4:5], 32, v149
	s_mov_b64 s[42:43], 0
	s_mov_b32 s70, s9
	s_mov_b32 s8, s71
	s_mov_b32 s71, s9
	s_waitcnt vmcnt(3)
	ds_write_b128 v0, v[130:133]
	s_waitcnt vmcnt(2)
	ds_write_b128 v2, v[134:137] offset:17408
	s_waitcnt vmcnt(1)
	ds_write_b128 v0, v[138:141] offset:8704
	s_waitcnt vmcnt(0)
	ds_write_b128 v2, v[142:145] offset:26624
	v_mov_b32_e32 v0, v1
	v_mov_b32_e32 v2, v1
	v_mov_b64_e32 v[64:65], v[14:15]
	v_mov_b64_e32 v[48:49], v[14:15]
	v_mov_b64_e32 v[32:33], v[14:15]
	v_mov_b64_e32 v[62:63], v[12:13]
	v_mov_b64_e32 v[60:61], v[10:11]
	v_mov_b64_e32 v[58:59], v[8:9]
	v_mov_b64_e32 v[56:57], v[6:7]
	v_mov_b64_e32 v[54:55], v[4:5]
	v_mov_b64_e32 v[52:53], v[2:3]
	v_mov_b64_e32 v[50:51], v[0:1]
	v_mov_b64_e32 v[46:47], v[12:13]
	v_mov_b64_e32 v[44:45], v[10:11]
	v_mov_b64_e32 v[42:43], v[8:9]
	v_mov_b64_e32 v[40:41], v[6:7]
	v_mov_b64_e32 v[38:39], v[4:5]
	v_mov_b64_e32 v[36:37], v[2:3]
	v_mov_b64_e32 v[34:35], v[0:1]
	v_mov_b64_e32 v[30:31], v[12:13]
	v_mov_b64_e32 v[28:29], v[10:11]
	v_mov_b64_e32 v[26:27], v[8:9]
	v_mov_b64_e32 v[24:25], v[6:7]
	v_mov_b64_e32 v[22:23], v[4:5]
	v_mov_b64_e32 v[20:21], v[2:3]
	v_mov_b64_e32 v[18:19], v[0:1]
	v_mov_b64_e32 v[16:17], v[14:15]
	v_mov_b64_e32 v[14:15], v[12:13]
	v_mov_b64_e32 v[12:13], v[10:11]
	v_mov_b64_e32 v[10:11], v[8:9]
	v_mov_b64_e32 v[8:9], v[6:7]
	v_mov_b64_e32 v[6:7], v[4:5]
	v_mov_b64_e32 v[4:5], v[2:3]
	v_mov_b64_e32 v[2:3], v[0:1]
	v_mov_b32_e32 v0, 0
	s_waitcnt lgkmcnt(0)
	s_barrier
	s_branch .LBB0_587
	s_nop 0
	s_nop 0
	s_nop 0
	s_nop 0
	s_nop 0
	s_nop 0
	s_nop 0
	s_nop 0
	s_nop 0
	s_nop 0
	s_nop 0
	s_nop 0
	s_nop 0
	s_nop 0
